# row-scale partial-sum loads in the P1/P3/P5/P10 epilogues use two 64-bit bases plus offset: immediates instead of eight address computations (on top of the P4 balance + P4 static priority)
# baseline (speedup 1.0000x reference)
;     __device__ __forceinline__ void operator()(const AccT& acc, const Unit& u, int wr, int wc, int fr, int fq) const {
;         const int row0 = u.pm * 256 + wr * 64 + fr, col0 = u.pn * 128 + wc * 32 + 8 * fq;
;         float rsv[2][4];
;         { f32x4 pv[2][4];
; #pragma unroll
;           for (int ai = 0; ai < 2; ++ai)
; #pragma unroll
;               for (int m = 0; m < 4; ++m) pv[ai][m] = *(const f32x4*)(ss + (size_t)(row0 + ai * 128 + m * 16) * 16 + fq * 4);
.LBB0_179:
	v_lshl_add_u32 v180, s89, 8, v184
	v_ashrrev_i32_e32 v181, 31, v180
	v_lshlrev_b64 v[130:131], 6, v[180:181]
	v_lshl_add_u64 v[130:131], v[160:161], 0, v[130:131]
	v_add_co_u32_e32 v226, vcc, 0x2000, v130
	global_load_dwordx4 v[188:191], v[130:131], off
	v_addc_co_u32_e32 v227, vcc, 0, v131, vcc
	global_load_dwordx4 v[206:209], v[130:131], off offset:1024
	global_load_dwordx4 v[150:153], v[130:131], off offset:2048
	global_load_dwordx4 v[146:149], v[130:131], off offset:3072
	global_load_dwordx4 v[142:145], v[226:227], off
	global_load_dwordx4 v[138:141], v[226:227], off offset:1024
	global_load_dwordx4 v[134:137], v[226:227], off offset:2048
	global_load_dwordx4 v[130:133], v[226:227], off offset:3072
	v_or_b32_e32 v178, 16, v180
	v_or_b32_e32 v176, 32, v180
	v_or_b32_e32 v174, 48, v180
	v_add_u32_e32 v172, 0x80, v180
	v_add_u32_e32 v170, 0x90, v180
	v_add_u32_e32 v168, 0xa0, v180
	v_add_u32_e32 v166, 0xb0, v180
	s_and_b64 vcc, exec, s[58:59]
	s_cbranch_vccz .LBB0_181
	s_barrier

;     __device__ __forceinline__ void operator()(const AccT& acc, const Unit& u, int wr, int wc, int fr, int fq) const {
;         const int row0 = u.pm * 256 + wr * 64 + fr, col0 = u.pn * 256 + wc * 32 + 8 * fq;
;         float rsv[2][4];
;         { f32x4 pv[2][4];
; #pragma unroll
;           for (int ai = 0; ai < 2; ++ai)
; #pragma unroll
;               for (int m = 0; m < 4; ++m) pv[ai][m] = *(const f32x4*)(ss + (size_t)(row0 + ai * 128 + m * 16) * 16 + fq * 4);
.LBB0_429:
	v_lshl_add_u32 v180, s90, 8, v183
	v_ashrrev_i32_e32 v181, 31, v180
	v_lshlrev_b64 v[130:131], 6, v[180:181]
	v_lshl_add_u64 v[130:131], v[160:161], 0, v[130:131]
	v_add_co_u32_e32 v226, vcc, 0x2000, v130
	global_load_dwordx4 v[190:193], v[130:131], off
	v_addc_co_u32_e32 v227, vcc, 0, v131, vcc
	global_load_dwordx4 v[206:209], v[130:131], off offset:1024
	global_load_dwordx4 v[150:153], v[130:131], off offset:2048
	global_load_dwordx4 v[146:149], v[130:131], off offset:3072
	global_load_dwordx4 v[142:145], v[226:227], off
	global_load_dwordx4 v[138:141], v[226:227], off offset:1024
	global_load_dwordx4 v[134:137], v[226:227], off offset:2048
	global_load_dwordx4 v[130:133], v[226:227], off offset:3072
	v_or_b32_e32 v178, 16, v180
	v_or_b32_e32 v176, 32, v180
	v_or_b32_e32 v174, 48, v180
	v_add_u32_e32 v172, 0x80, v180
	v_add_u32_e32 v170, 0x90, v180
	v_add_u32_e32 v168, 0xa0, v180
	v_add_u32_e32 v166, 0xb0, v180
	s_and_b64 vcc, exec, s[62:63]
	s_cbranch_vccz .LBB0_431
	s_barrier

;     __device__ __forceinline__ void operator()(const AccT& acc, const Unit& u, int wr, int wc, int fr, int fq) const {
;         const int row0 = u.pm * 256 + wr * 64 + fr, col0 = u.pn * 256 + wc * 32 + 8 * fq;
;         float rsv[2][4];
;         { f32x4 pv[2][4];
; #pragma unroll
;           for (int ai = 0; ai < 2; ++ai)
; #pragma unroll
;               for (int m = 0; m < 4; ++m) pv[ai][m] = *(const f32x4*)(ss + (size_t)(row0 + ai * 128 + m * 16) * 16 + fq * 4);
.LBB0_1441:
	v_lshl_add_u32 v180, s90, 8, v184
	v_ashrrev_i32_e32 v181, 31, v180
	v_lshlrev_b64 v[130:131], 6, v[180:181]
	v_lshl_add_u64 v[130:131], v[160:161], 0, v[130:131]
	v_add_co_u32_e32 v226, vcc, 0x2000, v130
	global_load_dwordx4 v[188:191], v[130:131], off
	v_addc_co_u32_e32 v227, vcc, 0, v131, vcc
	global_load_dwordx4 v[206:209], v[130:131], off offset:1024
	global_load_dwordx4 v[150:153], v[130:131], off offset:2048
	global_load_dwordx4 v[146:149], v[130:131], off offset:3072
	global_load_dwordx4 v[142:145], v[226:227], off
	global_load_dwordx4 v[138:141], v[226:227], off offset:1024
	global_load_dwordx4 v[134:137], v[226:227], off offset:2048
	global_load_dwordx4 v[130:133], v[226:227], off offset:3072
	v_or_b32_e32 v178, 16, v180
	v_or_b32_e32 v176, 32, v180
	v_or_b32_e32 v174, 48, v180
	v_add_u32_e32 v172, 0x80, v180
	v_add_u32_e32 v170, 0x90, v180
	v_add_u32_e32 v168, 0xa0, v180
	v_add_u32_e32 v166, 0xb0, v180
	s_and_b64 vcc, exec, s[66:67]
	s_cbranch_vccz .LBB0_1443
	s_barrier

;     __device__ __forceinline__ void operator()(const AccT& acc, const Unit& u, int wr, int wc, int fr, int fq) const {
;         const int row0 = u.pm * 256 + wr * 64 + fr, col0 = u.pn * 128 + wc * 32 + 8 * fq;
;         float rsv[2][4];
;         { f32x4 pv[2][4];
; #pragma unroll
;           for (int ai = 0; ai < 2; ++ai)
; #pragma unroll
;               for (int m = 0; m < 4; ++m) pv[ai][m] = *(const f32x4*)(ss + (size_t)(row0 + ai * 128 + m * 16) * 16 + fq * 4);
.LBB0_1909:
	v_lshl_add_u32 v180, s90, 8, v184
	v_ashrrev_i32_e32 v181, 31, v180
	v_lshlrev_b64 v[130:131], 6, v[180:181]
	v_lshl_add_u64 v[130:131], v[160:161], 0, v[130:131]
	v_add_co_u32_e32 v226, vcc, 0x2000, v130
	global_load_dwordx4 v[188:191], v[130:131], off
	v_addc_co_u32_e32 v227, vcc, 0, v131, vcc
	global_load_dwordx4 v[206:209], v[130:131], off offset:1024
	global_load_dwordx4 v[150:153], v[130:131], off offset:2048
	global_load_dwordx4 v[146:149], v[130:131], off offset:3072
	global_load_dwordx4 v[142:145], v[226:227], off
	global_load_dwordx4 v[138:141], v[226:227], off offset:1024
	global_load_dwordx4 v[134:137], v[226:227], off offset:2048
	global_load_dwordx4 v[130:133], v[226:227], off offset:3072
	v_or_b32_e32 v178, 16, v180
	v_or_b32_e32 v176, 32, v180
	v_or_b32_e32 v174, 48, v180
	v_add_u32_e32 v172, 0x80, v180
	v_add_u32_e32 v170, 0x90, v180
	v_add_u32_e32 v168, 0xa0, v180
	v_add_u32_e32 v166, 0xb0, v180
	s_and_b64 vcc, exec, s[62:63]
	s_cbranch_vccz .LBB0_1911
	s_barrier
